# 768-tile GEMMs: tile order by rounds so the first round uses only the earliest-finished row panels; panel-ready waits without the acquire invalidate
# baseline (speedup 1.0000x reference)
.LBB0_1702:
	s_cmpk_lt_i32 s3, 0x300
	s_cselect_b64 s[4:5], -1, 0
	s_cmpk_gt_i32 s3, 0x2ff
	v_readfirstlane_b32 s33, v59
	s_waitcnt lgkmcnt(0)
	s_barrier
	s_cbranch_scc1 .LBB0_1704
	s_ashr_i32 s6, s3, 31
	s_lshr_b32 s6, s6, 29
	s_add_i32 s6, s3, s6
	s_ashr_i32 s7, s6, 3
	s_and_b32 s6, s6, -8
	s_sub_i32 s6, s3, s6
	s_lshl_b32 s6, s6, 5
	s_and_b32 s8, s7, 31
	s_add_i32 s6, s6, s8
	s_andn2_b32 s8, s7, 31
	s_lshl_b32 s8, s8, 3
	s_add_i32 s6, s6, s8
	s_ashr_i32 s7, s6, 31
	s_lshr_b32 s7, s7, 25
	s_add_i32 s7, s6, s7
	s_ashr_i32 s8, s7, 7
	s_lshl_b32 s8, s8, 3
	s_sub_i32 s9, 48, s8
	s_min_u32 s9, s9, 8
	s_and_b32 s7, s7, 0xffffff80
	s_sub_i32 s12, s6, s7
	v_cvt_f32_ubyte0_e32 v1, s9
	v_cvt_f32_i32_e32 v0, s12
	v_rcp_iflag_f32_e32 v2, v1
	s_ashr_i32 s6, s12, 30
	s_or_b32 s13, s6, 1
	v_mul_f32_e32 v2, v0, v2
	v_trunc_f32_e32 v2, v2
	v_fma_f32 v0, -v2, v1, v0
	v_cvt_i32_f32_e32 v2, v2
	v_cmp_ge_f32_e64 s[6:7], |v0|, v1
	s_and_b64 s[6:7], s[6:7], exec
	s_cselect_b32 s6, s13, 0
	v_readfirstlane_b32 s7, v2
	s_add_i32 s6, s7, s6
	s_sext_i32_i8 s42, s6
	s_mul_i32 s6, s6, s9
	s_sub_i32 s6, s12, s6
	s_sext_i32_i8 s6, s6
	s_add_i32 s44, s8, s6

.LBB0_1726:
	s_add_i32 s82, s82, 1
	s_mul_i32 s8, s82, s75
	s_mul_hi_u32 s9, s82, s2
	s_add_i32 s9, s9, s8
	s_mul_i32 s8, s82, s2
	s_add_u32 s10, s8, s3
	s_addc_u32 s11, s9, s76
	v_cmp_gt_i64_e64 s[8:9], s[10:11], v[140:141]
	s_and_b64 vcc, exec, s[8:9]
	s_cbranch_vccnz .LBB0_1728
	s_ashr_i32 s11, s10, 31
	s_lshr_b32 s11, s11, 29
	s_add_i32 s11, s10, s11
	s_ashr_i32 s20, s11, 3
	s_and_b32 s11, s11, -8
	s_sub_i32 s10, s10, s11
	s_lshl_b32 s10, s10, 5
	s_and_b32 s11, s20, 31
	s_add_i32 s10, s10, s11
	s_andn2_b32 s11, s20, 31
	s_lshl_b32 s11, s11, 3
	s_add_i32 s10, s10, s11
	s_ashr_i32 s11, s10, 31
	s_lshr_b32 s11, s11, 25
	s_add_i32 s11, s10, s11
	s_ashr_i32 s20, s11, 7
	s_lshl_b32 s20, s20, 3
	s_sub_i32 s30, 48, s20
	s_min_i32 s31, s30, 8
	s_abs_i32 s30, s31
	v_cvt_f32_u32_e32 v0, s30
	s_sub_i32 s35, 0, s30
	s_and_b32 s11, s11, 0xffffff80
	s_sub_i32 s10, s10, s11
	v_rcp_iflag_f32_e32 v0, v0
	s_abs_i32 s11, s10
	s_xor_b32 s34, s10, s31
	s_ashr_i32 s34, s34, 31
	v_mul_f32_e32 v0, 0x4f7ffffe, v0
	v_cvt_u32_f32_e32 v0, v0
	s_nop 0
	v_readfirstlane_b32 s36, v0
	s_mul_i32 s35, s35, s36
	s_mul_hi_u32 s35, s36, s35
	s_add_i32 s36, s36, s35
	s_mul_hi_u32 s35, s11, s36
	s_mul_i32 s36, s35, s30
	s_sub_i32 s11, s11, s36
	s_add_i32 s37, s35, 1
	s_sub_i32 s36, s11, s30
	s_cmp_ge_u32 s11, s30
	s_cselect_b32 s35, s37, s35
	s_cselect_b32 s11, s36, s11
	s_add_i32 s36, s35, 1
	s_cmp_ge_u32 s11, s30
	s_cselect_b32 s11, s36, s35
	s_xor_b32 s11, s11, s34
	s_sub_i32 s30, s11, s34
	s_mul_i32 s11, s30, s31
	s_sub_i32 s10, s10, s11
	s_add_i32 s34, s10, s20

.LBB0_2092:
	s_cmpk_lt_i32 s2, 0x300
	s_cselect_b64 s[4:5], -1, 0
	s_cmpk_gt_i32 s2, 0x2ff
	v_readfirstlane_b32 s33, v59
	s_waitcnt lgkmcnt(0)
	s_barrier
	s_cbranch_scc1 .LBB0_2094
	s_ashr_i32 s6, s2, 31
	s_lshr_b32 s6, s6, 29
	s_add_i32 s6, s2, s6
	s_ashr_i32 s7, s6, 3
	s_and_b32 s6, s6, -8
	s_sub_i32 s6, s2, s6
	s_lshl_b32 s6, s6, 5
	s_and_b32 s8, s7, 31
	s_add_i32 s6, s6, s8
	s_andn2_b32 s8, s7, 31
	s_lshl_b32 s8, s8, 3
	s_add_i32 s6, s6, s8
	s_mul_hi_i32 s7, s6, 0x2aaaaaab
	s_lshr_b32 s8, s7, 31
	s_ashr_i32 s7, s7, 4
	s_add_i32 s7, s7, s8
	s_lshl_b32 s8, s7, 3
	s_sub_i32 s9, 64, s8
	s_min_u32 s9, s9, 8
	s_mulk_i32 s7, 0x60
	s_sub_i32 s12, s6, s7
	v_cvt_f32_ubyte0_e32 v1, s9
	v_cvt_f32_i32_e32 v0, s12
	v_rcp_iflag_f32_e32 v2, v1
	s_ashr_i32 s6, s12, 30
	s_or_b32 s13, s6, 1
	v_mul_f32_e32 v2, v0, v2
	v_trunc_f32_e32 v2, v2
	v_fma_f32 v0, -v2, v1, v0
	v_cvt_i32_f32_e32 v2, v2
	v_cmp_ge_f32_e64 s[6:7], |v0|, v1
	s_and_b64 s[6:7], s[6:7], exec
	s_cselect_b32 s6, s13, 0
	v_readfirstlane_b32 s7, v2
	s_add_i32 s6, s7, s6
	s_sext_i32_i8 s14, s6
	s_mul_i32 s6, s6, s9
	s_sub_i32 s6, s12, s6
	s_sext_i32_i8 s6, s6
	s_add_i32 s54, s8, s6

.LBB0_2116:
	s_add_i32 s73, s73, 1
	s_mul_i32 s8, s73, s66
	s_mul_hi_u32 s9, s73, s3
	s_add_i32 s9, s9, s8
	s_mul_i32 s8, s73, s3
	s_add_u32 s30, s8, s2
	s_addc_u32 s31, s9, s67
	v_cmp_gt_i64_e64 s[8:9], s[30:31], v[108:109]
	v_cmp_lt_i64_e64 s[10:11], s[30:31], v[106:107]
	s_and_b64 vcc, exec, s[8:9]
	s_cbranch_vccnz .LBB0_2118
	s_ashr_i32 s15, s30, 31
	s_lshr_b32 s15, s15, 29
	s_add_i32 s15, s30, s15
	s_ashr_i32 s22, s15, 3
	s_and_b32 s15, s15, -8
	s_sub_i32 s15, s30, s15
	s_lshl_b32 s15, s15, 5
	s_and_b32 s28, s22, 31
	s_add_i32 s15, s15, s28
	s_andn2_b32 s28, s22, 31
	s_lshl_b32 s28, s28, 3
	s_add_i32 s15, s15, s28
	s_mul_hi_i32 s22, s15, 0x2aaaaaab
	s_lshr_b32 s28, s22, 31
	s_ashr_i32 s22, s22, 4
	s_add_i32 s22, s22, s28
	s_lshl_b32 s29, s22, 3
	s_sub_i32 s28, 64, s29
	s_min_i32 s30, s28, 8
	s_abs_i32 s28, s30
	v_cvt_f32_u32_e32 v0, s28
	s_sub_i32 s34, 0, s28
	s_mulk_i32 s22, 0x60
	s_sub_i32 s15, s15, s22
	v_rcp_iflag_f32_e32 v0, v0
	s_abs_i32 s22, s15
	s_xor_b32 s31, s15, s30
	s_ashr_i32 s31, s31, 31
	v_mul_f32_e32 v0, 0x4f7ffffe, v0
	v_cvt_u32_f32_e32 v0, v0
	s_nop 0
	v_readfirstlane_b32 s35, v0
	s_mul_i32 s34, s34, s35
	s_mul_hi_u32 s34, s35, s34
	s_add_i32 s35, s35, s34
	s_mul_hi_u32 s34, s22, s35
	s_mul_i32 s35, s34, s28
	s_sub_i32 s22, s22, s35
	s_add_i32 s36, s34, 1
	s_sub_i32 s35, s22, s28
	s_cmp_ge_u32 s22, s28
	s_cselect_b32 s34, s36, s34
	s_cselect_b32 s22, s35, s22
	s_add_i32 s35, s34, 1
	s_cmp_ge_u32 s22, s28
	s_cselect_b32 s22, s35, s34
	s_xor_b32 s22, s22, s31
	s_sub_i32 s28, s22, s31
	s_mul_i32 s22, s28, s30
	s_sub_i32 s15, s15, s22
	s_add_i32 s74, s15, s29

.LBB0_3338:
	s_cmpk_lt_i32 s2, 0x300
	s_cselect_b64 s[4:5], -1, 0
	s_cmpk_gt_i32 s2, 0x2ff
	v_readfirstlane_b32 s33, v59
	s_waitcnt lgkmcnt(0)
	s_barrier
	s_cbranch_scc1 .LBB0_3340
	s_ashr_i32 s6, s2, 31
	s_lshr_b32 s6, s6, 29
	s_add_i32 s6, s2, s6
	s_ashr_i32 s7, s6, 3
	s_and_b32 s6, s6, -8
	s_sub_i32 s6, s2, s6
	s_lshl_b32 s6, s6, 5
	s_and_b32 s8, s7, 31
	s_add_i32 s6, s6, s8
	s_andn2_b32 s8, s7, 31
	s_lshl_b32 s8, s8, 3
	s_add_i32 s6, s6, s8
	s_ashr_i32 s7, s6, 31
	s_lshr_b32 s7, s7, 25
	s_add_i32 s7, s6, s7
	s_ashr_i32 s8, s7, 7
	s_lshl_b32 s8, s8, 3
	s_sub_i32 s9, 48, s8
	s_min_u32 s9, s9, 8
	s_and_b32 s7, s7, 0xffffff80
	s_sub_i32 s12, s6, s7
	v_cvt_f32_ubyte0_e32 v1, s9
	v_cvt_f32_i32_e32 v0, s12
	v_rcp_iflag_f32_e32 v2, v1
	s_ashr_i32 s6, s12, 30
	s_or_b32 s13, s6, 1
	v_mul_f32_e32 v2, v0, v2
	v_trunc_f32_e32 v2, v2
	v_fma_f32 v0, -v2, v1, v0
	v_cvt_i32_f32_e32 v2, v2
	v_cmp_ge_f32_e64 s[6:7], |v0|, v1
	s_and_b64 s[6:7], s[6:7], exec
	s_cselect_b32 s6, s13, 0
	v_readfirstlane_b32 s7, v2
	s_add_i32 s6, s7, s6
	s_sext_i32_i8 s42, s6
	s_mul_i32 s6, s6, s9
	s_sub_i32 s6, s12, s6
	s_sext_i32_i8 s6, s6
	s_add_i32 s44, s8, s6

.LBB0_3362:
	s_add_i32 s82, s82, 1
	s_mul_i32 s8, s82, s75
	s_mul_hi_u32 s9, s82, s3
	s_add_i32 s9, s9, s8
	s_mul_i32 s8, s82, s3
	s_add_u32 s10, s8, s2
	s_addc_u32 s11, s9, s76
	v_cmp_gt_i64_e64 s[8:9], s[10:11], v[140:141]
	s_and_b64 vcc, exec, s[8:9]
	s_cbranch_vccnz .LBB0_3364
	s_ashr_i32 s11, s10, 31
	s_lshr_b32 s11, s11, 29
	s_add_i32 s11, s10, s11
	s_ashr_i32 s20, s11, 3
	s_and_b32 s11, s11, -8
	s_sub_i32 s10, s10, s11
	s_lshl_b32 s10, s10, 5
	s_and_b32 s11, s20, 31
	s_add_i32 s10, s10, s11
	s_andn2_b32 s11, s20, 31
	s_lshl_b32 s11, s11, 3
	s_add_i32 s10, s10, s11
	s_ashr_i32 s11, s10, 31
	s_lshr_b32 s11, s11, 25
	s_add_i32 s11, s10, s11
	s_ashr_i32 s20, s11, 7
	s_lshl_b32 s20, s20, 3
	s_sub_i32 s30, 48, s20
	s_min_i32 s31, s30, 8
	s_abs_i32 s30, s31
	v_cvt_f32_u32_e32 v0, s30
	s_sub_i32 s35, 0, s30
	s_and_b32 s11, s11, 0xffffff80
	s_sub_i32 s10, s10, s11
	v_rcp_iflag_f32_e32 v0, v0
	s_abs_i32 s11, s10
	s_xor_b32 s34, s10, s31
	s_ashr_i32 s34, s34, 31
	v_mul_f32_e32 v0, 0x4f7ffffe, v0
	v_cvt_u32_f32_e32 v0, v0
	s_nop 0
	v_readfirstlane_b32 s36, v0
	s_mul_i32 s35, s35, s36
	s_mul_hi_u32 s35, s36, s35
	s_add_i32 s36, s36, s35
	s_mul_hi_u32 s35, s11, s36
	s_mul_i32 s36, s35, s30
	s_sub_i32 s11, s11, s36
	s_add_i32 s37, s35, 1
	s_sub_i32 s36, s11, s30
	s_cmp_ge_u32 s11, s30
	s_cselect_b32 s35, s37, s35
	s_cselect_b32 s11, s36, s11
	s_add_i32 s36, s35, 1
	s_cmp_ge_u32 s11, s30
	s_cselect_b32 s11, s36, s35
	s_xor_b32 s11, s11, s34
	s_sub_i32 s30, s11, s34
	s_mul_i32 s11, s30, s31
	s_sub_i32 s10, s10, s11
	s_add_i32 s34, s10, s20
